# grid barrier XCD leader: cache invalidate issued after the cross-XCD arrive atomic instead of before it (overlaps the atomic round trip)
# speedup vs baseline: 1.0060x; 1.0015x over previous
.LBB0_860:
	s_or_b64 exec, exec, s[8:9]
	buffer_inv sc1
	v_cvt_f32_u32_e32 v3, v0
	s_waitcnt vmcnt(0)
	v_readfirstlane_b32 s4, v2
	s_add_u32 s8, s90, 0x3500
	s_addc_u32 s9, s91, 0
	v_rcp_iflag_f32_e32 v3, v3
	v_add_u32_e32 v1, s4, v1
	v_add_u32_e32 v4, 1, v1
	s_mov_b64 s[10:11], -1
	v_mul_f32_e32 v2, 0x4f7ffffe, v3
	v_cvt_u32_f32_e32 v2, v2
	v_sub_u32_e32 v3, 0, v0
	v_mul_lo_u32 v3, v3, v2
	v_mul_hi_u32 v3, v2, v3
	v_add_u32_e32 v2, v2, v3
	v_mul_hi_u32 v2, v1, v2
	v_mul_lo_u32 v3, v2, v0
	v_sub_u32_e32 v1, v1, v3
	v_add_u32_e32 v5, 1, v2
	v_cmp_ge_u32_e32 vcc, v1, v0
	v_sub_u32_e32 v3, v1, v0
	s_nop 0
	v_cndmask_b32_e32 v2, v2, v5, vcc
	v_cndmask_b32_e32 v1, v1, v3, vcc
	v_add_u32_e32 v3, 1, v2
	v_cmp_ge_u32_e32 vcc, v1, v0
	s_nop 1
	v_cndmask_b32_e32 v2, v2, v3, vcc
	v_mul_lo_u32 v1, v0, v2
	v_add_u32_e32 v0, v1, v0
	v_cmp_ne_u32_e32 vcc, v4, v0
	v_mov_b64_e32 v[0:1], s[8:9]
	s_and_saveexec_b64 s[4:5], vcc
	s_cbranch_execz .LBB0_872
	v_mov_b32_e32 v0, 0
	global_load_dword v1, v0, s[8:9] sc1
	s_mov_b64 s[14:15], 0
	s_waitcnt vmcnt(0)
	v_cmp_eq_u32_e32 vcc, v1, v2
	s_and_saveexec_b64 s[12:13], vcc
	s_cbranch_execz .LBB0_871
	s_add_u32 s10, s90, 0x200
	s_addc_u32 s11, s91, 0
	s_mov_b32 s24, 1
	s_branch .LBB0_864

.LBB0_2118:
	s_or_b64 exec, exec, s[8:9]
	buffer_inv sc1
	v_cvt_f32_u32_e32 v3, v0
	s_waitcnt vmcnt(0)
	v_readfirstlane_b32 s6, v2
	s_add_u32 s8, s90, 0x3500
	s_addc_u32 s9, s91, 0
	v_rcp_iflag_f32_e32 v3, v3
	v_add_u32_e32 v1, s6, v1
	v_add_u32_e32 v4, 1, v1
	s_mov_b64 s[10:11], -1
	v_mul_f32_e32 v2, 0x4f7ffffe, v3
	v_cvt_u32_f32_e32 v2, v2
	v_sub_u32_e32 v3, 0, v0
	v_mul_lo_u32 v3, v3, v2
	v_mul_hi_u32 v3, v2, v3
	v_add_u32_e32 v2, v2, v3
	v_mul_hi_u32 v2, v1, v2
	v_mul_lo_u32 v3, v2, v0
	v_sub_u32_e32 v1, v1, v3
	v_add_u32_e32 v5, 1, v2
	v_cmp_ge_u32_e32 vcc, v1, v0
	v_sub_u32_e32 v3, v1, v0
	s_nop 0
	v_cndmask_b32_e32 v2, v2, v5, vcc
	v_cndmask_b32_e32 v1, v1, v3, vcc
	v_add_u32_e32 v3, 1, v2
	v_cmp_ge_u32_e32 vcc, v1, v0
	s_nop 1
	v_cndmask_b32_e32 v2, v2, v3, vcc
	v_mul_lo_u32 v1, v0, v2
	v_add_u32_e32 v0, v1, v0
	v_cmp_ne_u32_e32 vcc, v4, v0
	v_mov_b64_e32 v[0:1], s[8:9]
	s_and_saveexec_b64 s[6:7], vcc
	s_cbranch_execz .LBB0_2130
	v_mov_b32_e32 v0, 0
	global_load_dword v1, v0, s[8:9] sc1
	s_mov_b64 s[14:15], 0
	s_waitcnt vmcnt(0)
	v_cmp_eq_u32_e32 vcc, v1, v2
	s_and_saveexec_b64 s[12:13], vcc
	s_cbranch_execz .LBB0_2129
	s_add_u32 s10, s90, 0x200
	s_addc_u32 s11, s91, 0
	s_mov_b32 s24, 1
	s_branch .LBB0_2122
